# v9 + attention unit kv-head swap (lighter pooling on sample-unit WGs) + knorm loads issued together in sample unit
# speedup vs baseline: 1.0225x; 1.0009x over previous
; #define LAS __attribute__((address_space(3)))
; __device__ __forceinline__ void attn_macro(const Params& p, int l, LAS unsigned char* lds, int b, int cg, int kvh) {
;     int tid = threadIdx.x; asm volatile("" : "+v"(tid));
;     const int wid = __builtin_amdgcn_readfirstlane(tid >> 6);
;     int lane = tid & 63; asm volatile("" : "+v"(lane));
;     const int q32 = lane & 31, hi = lane >> 5;
;     LAS bf16_t* Ks = (LAS bf16_t*)lds; LAS bf16_t* Vt = (LAS bf16_t*)(lds + M_VT); LAS float* wsc = (LAS float*)(lds + M_WSC) + wid * 32;
;     const bf16_t* P = (const bf16_t*)(p.ws + WS_PROJ);
;     bf16_t* AD = (bf16_t*)(p.ws + WS_AD);
;     const int c0 = 4 * cg;
;     const long rowb = (long)b * SEQ;
;     const int gq = wid >> 1, half = wid & 1, h = kvh * 4 + gq, tq = half * 32 + q32;
;     u32x4 qraw[4];
; #pragma unroll
;     for (int i = 0; i < 4; ++i) qraw[i] = *(const u32x4*)(P + (size_t)(rowb + c0 * 64 + half * 32 + i * 8 + (lane >> 3)) * INW + h * 64 + (lane & 7) * 8);
;     u32x4 kraw[6], vraw[6];
; #pragma unroll
;     for (int it = 0; it < 6; ++it) {
;         const int idx = it * 512 + tid, j = idx >> 3, ch = idx & 7, tk = c0 * 64 - 128 + j;
;         kraw[it] = (u32x4){0u, 0u, 0u, 0u}; vraw[it] = kraw[it];
;         if (tk >= 0) { const size_t o = (size_t)(rowb + tk) * INW + kvh * 64 + ch * 8; kraw[it] = *(const u32x4*)(P + o + 512); vraw[it] = *(const u32x4*)(P + o + 640); }
;     }
; __global__ void __launch_bounds__(512) mk_fwd(Params p0) {
;     ...
;                 else { const int q = idx - 16; attn_macro(p, l, lds, q >> 7, q & 63, (q >> 6) & 1); }
.LBB0_287:
	s_cmp_gt_i32 s23, 15
	s_mov_b64 s[0:1], -1
	s_cbranch_scc0 .LBB0_413
	s_add_i32 s10, s23, -16
	v_mov_b32_e32 v136, v222
	s_bfe_u32 s12, s10, 0x10006
	s_xor_b32 s12, s12, 1
	s_lshr_b32 s7, s10, 7
	v_readfirstlane_b32 s0, v136
	s_and_b32 s11, s10, 63
	s_ashr_i32 s13, s0, 6
	s_ashr_i32 s14, s0, 7
	s_lshl_b32 s0, s12, 2
	s_lshl_b32 s15, s7, 14
	s_add_i32 s14, s14, s0
	s_lshl_b32 s0, s13, 5
	s_lshl_b32 s17, s11, 8
	s_and_b32 s16, s0, 32
	s_or_b32 s0, s17, s15
	s_or_b32 s96, s0, s16
	s_lshl_b32 s0, s14, 6
	v_and_b32_e32 v137, 63, v136
	s_ashr_i32 s1, s0, 31
	s_lshl_b64 s[2:3], s[0:1], 1
	v_lshlrev_b32_e32 v0, 3, v137
	v_ashrrev_i32_e32 v126, 3, v137
	s_add_u32 s0, s84, s2
	v_and_b32_e32 v0, 56, v0
	v_ashrrev_i32_e32 v127, 31, v126
	s_addc_u32 s1, s85, s3
	v_lshlrev_b32_e32 v56, 1, v0
	v_mov_b32_e32 v57, v97
	v_lshl_add_u64 v[0:1], s[0:1], 0, v[56:57]
	v_lshl_add_u64 v[2:3], s[96:97], 0, v[126:127]
	v_mad_u64_u32 v[4:5], s[8:9], v2, s89, v[0:1]
	s_or_b32 s8, s96, 8
	s_mov_b32 s9, s97
	v_mad_i32_i24 v5, v3, s89, v5
	v_lshl_add_u64 v[2:3], s[8:9], 0, v[126:127]
	v_mad_u64_u32 v[6:7], s[8:9], v2, s89, v[0:1]
	s_or_b32 s8, s96, 16
	s_mov_b32 s9, s97
	v_mad_i32_i24 v7, v3, s89, v7
	v_lshl_add_u64 v[2:3], s[8:9], 0, v[126:127]
	global_load_dwordx4 v[98:101], v[4:5], off
	global_load_dwordx4 v[102:105], v[6:7], off
	v_mad_u64_u32 v[4:5], s[8:9], v2, s89, v[0:1]
	s_or_b32 s96, s96, 24
	v_mad_i32_i24 v5, v3, s89, v5
	v_lshl_add_u64 v[2:3], s[96:97], 0, v[126:127]
	v_mad_u64_u32 v[0:1], s[8:9], v2, s89, v[0:1]
	v_mad_i32_i24 v1, v3, s89, v1
	global_load_dwordx4 v[106:109], v[4:5], off
	global_load_dwordx4 v[110:113], v[0:1], off
	s_addk_i32 s17, 0xff80
	v_lshlrev_b32_e32 v138, 3, v136
	s_lshl_b32 s8, s12, 7
	v_and_b32_e32 v57, 56, v138
	s_add_u32 s8, s84, s8
	v_ashrrev_i32_e32 v73, 3, v136
	s_addc_u32 s9, s85, 0
	v_lshlrev_b32_e32 v96, 1, v57
	v_add_u32_e32 v0, s17, v73
	v_lshl_add_u64 v[48:49], s[8:9], 0, v[96:97]
	v_cmp_lt_i32_e32 vcc, -1, v0
	v_mov_b32_e32 v32, 0
	v_mov_b32_e32 v44, 0
	v_mov_b32_e32 v45, 0
	v_mov_b32_e32 v46, 0
	v_mov_b32_e32 v47, 0
	v_mov_b32_e32 v40, 0
	v_mov_b32_e32 v41, 0
	v_mov_b32_e32 v42, 0
	v_mov_b32_e32 v43, 0
	s_and_saveexec_b64 s[8:9], vcc
	s_cbranch_execz .LBB0_290
	v_add_u32_e32 v0, s15, v0
	v_mad_u64_u32 v[0:1], s[40:41], v0, s89, v[48:49]
	global_load_dwordx4 v[40:43], v[0:1], off offset:1024
	global_load_dwordx4 v[44:47], v[0:1], off offset:1280

; __device__ __forceinline__ void attn_unit(const Params& p, int l, LAS unsigned char* lds, bool sample, int b, int c, int kvh) {
;     ...
;         float ss = 0.f;
; #pragma unroll
;         for (int i = 0; i < 8; ++i) ss += kf[i] * kf[i];
;         ss += __shfl_xor(ss, 1); ss += __shfl_xor(ss, 2); ss += __shfl_xor(ss, 4);
;         if (fromproj) { const float sc = __builtin_amdgcn_rsqf(ss * (1.0f / 64.0f) + EPS);
; #pragma unroll
;             for (int i = 0; i < 8; ++i) kf[i] = kf[i] * sc * knorm[ch * 8 + i]; }
.LBB0_588:
	s_or_b64 exec, exec, s[0:1]
	v_mul_f32_e32 v56, v37, v37
	v_fmac_f32_e32 v56, v36, v36
	v_fmac_f32_e32 v56, v38, v38
	v_fmac_f32_e32 v56, v39, v39
	v_fmac_f32_e32 v56, v32, v32
	v_fmac_f32_e32 v56, v33, v33
	v_fmac_f32_e32 v56, v34, v34
	v_fmac_f32_e32 v56, v35, v35
	ds_bpermute_b32 v57, v91, v56
	s_waitcnt lgkmcnt(0)
	v_add_f32_e32 v56, v56, v57
	ds_bpermute_b32 v57, v93, v56
	s_waitcnt lgkmcnt(0)
	v_add_f32_e32 v56, v56, v57
	ds_bpermute_b32 v57, v99, v56
	s_and_saveexec_b64 s[0:1], vcc
	s_cbranch_execz .LBB0_590
	global_load_dwordx2 v[58:59], v104, s[50:51]
	s_waitcnt lgkmcnt(0)
	v_add_f32_e32 v56, v56, v57
	v_fmamk_f32 v56, v56, 0x3c800000, v223
	v_rsq_f32_e32 v56, v56
	v_mov_b32_e32 v83, v97
	v_mov_b32_e32 v81, v97
	v_lshl_add_u64 v[250:251], v[96:97], 2, s[50:51]
	global_load_dwordx2 v[250:251], v[250:251], off
	v_lshl_add_u64 v[252:253], v[82:83], 2, s[50:51]
	global_load_dwordx2 v[252:253], v[252:253], off
	v_lshl_add_u64 v[254:255], v[80:81], 2, s[50:51]
	global_load_dwordx2 v[254:255], v[254:255], off
	v_pk_mul_f32 v[36:37], v[36:37], v[56:57] op_sel_hi:[1,0]
	v_pk_mul_f32 v[38:39], v[38:39], v[56:57] op_sel_hi:[1,0]
	v_pk_mul_f32 v[32:33], v[32:33], v[56:57] op_sel_hi:[1,0]
	v_pk_mul_f32 v[34:35], v[34:35], v[56:57] op_sel_hi:[1,0]
	s_waitcnt vmcnt(0)
	v_pk_mul_f32 v[36:37], v[36:37], v[58:59]
	v_pk_mul_f32 v[38:39], v[38:39], v[250:251]
	v_pk_mul_f32 v[32:33], v[32:33], v[252:253]
	v_pk_mul_f32 v[34:35], v[34:35], v[254:255]

; __device__ __forceinline__ void attn_unit(const Params& p, int l, LAS unsigned char* lds, bool sample, int b, int c, int kvh) {
;     ...
;         float ss = 0.f;
; #pragma unroll
;         for (int i = 0; i < 8; ++i) ss += kf[i] * kf[i];
;         ss += __shfl_xor(ss, 1); ss += __shfl_xor(ss, 2); ss += __shfl_xor(ss, 4);
;         if (fromproj) { const float sc = __builtin_amdgcn_rsqf(ss * (1.0f / 64.0f) + EPS);
; #pragma unroll
;             for (int i = 0; i < 8; ++i) kf[i] = kf[i] * sc * knorm[ch * 8 + i]; }
.LBB0_598:
	s_or_b64 exec, exec, s[0:1]
	v_mul_f32_e32 v32, v21, v21
	v_fmac_f32_e32 v32, v20, v20
	v_fmac_f32_e32 v32, v22, v22
	v_fmac_f32_e32 v32, v23, v23
	v_fmac_f32_e32 v32, v16, v16
	v_fmac_f32_e32 v32, v17, v17
	v_fmac_f32_e32 v32, v18, v18
	v_fmac_f32_e32 v32, v19, v19
	ds_bpermute_b32 v33, v91, v32
	s_waitcnt lgkmcnt(0)
	v_add_f32_e32 v32, v32, v33
	ds_bpermute_b32 v33, v93, v32
	s_waitcnt lgkmcnt(0)
	v_add_f32_e32 v32, v32, v33
	ds_bpermute_b32 v33, v99, v32
	s_and_saveexec_b64 s[0:1], vcc
	s_cbranch_execz .LBB0_600
	global_load_dwordx2 v[34:35], v104, s[50:51]
	s_waitcnt lgkmcnt(0)
	v_add_f32_e32 v32, v32, v33
	v_fmamk_f32 v32, v32, 0x3c800000, v223
	v_rsq_f32_e32 v32, v32
	v_mov_b32_e32 v83, v97
	v_mov_b32_e32 v81, v97
	v_lshl_add_u64 v[250:251], v[96:97], 2, s[50:51]
	global_load_dwordx2 v[250:251], v[250:251], off
	v_lshl_add_u64 v[252:253], v[82:83], 2, s[50:51]
	global_load_dwordx2 v[252:253], v[252:253], off
	v_lshl_add_u64 v[254:255], v[80:81], 2, s[50:51]
	global_load_dwordx2 v[254:255], v[254:255], off
	v_pk_mul_f32 v[20:21], v[20:21], v[32:33] op_sel_hi:[1,0]
	v_pk_mul_f32 v[22:23], v[22:23], v[32:33] op_sel_hi:[1,0]
	v_pk_mul_f32 v[16:17], v[16:17], v[32:33] op_sel_hi:[1,0]
	v_pk_mul_f32 v[18:19], v[18:19], v[32:33] op_sel_hi:[1,0]
	s_waitcnt vmcnt(0)
	v_pk_mul_f32 v[20:21], v[20:21], v[34:35]
	v_pk_mul_f32 v[22:23], v[22:23], v[250:251]
	v_pk_mul_f32 v[16:17], v[16:17], v[252:253]
	v_pk_mul_f32 v[18:19], v[18:19], v[254:255]

; __global__ void __launch_bounds__(512) mk_fwd(Params p0) {
	.amdhsa_kernel _Z6mk_fwd6Params
		.amdhsa_group_segment_fixed_size 0
		.amdhsa_private_segment_fixed_size 0
		.amdhsa_kernarg_size 448
		.amdhsa_user_sgpr_count 2
		.amdhsa_user_sgpr_dispatch_ptr 0
		.amdhsa_user_sgpr_queue_ptr 0
		.amdhsa_user_sgpr_kernarg_segment_ptr 1
		.amdhsa_user_sgpr_dispatch_id 0
		.amdhsa_user_sgpr_kernarg_preload_length 0
		.amdhsa_user_sgpr_kernarg_preload_offset 0
		.amdhsa_user_sgpr_private_segment_size 0
		.amdhsa_uses_dynamic_stack 0
		.amdhsa_enable_private_segment 0
		.amdhsa_system_sgpr_workgroup_id_x 1
		.amdhsa_system_sgpr_workgroup_id_y 0
		.amdhsa_system_sgpr_workgroup_id_z 0
		.amdhsa_system_sgpr_workgroup_info 0
		.amdhsa_system_vgpr_workitem_id 2
		.amdhsa_next_free_vgpr 256
		.amdhsa_next_free_sgpr 100
		.amdhsa_accum_offset 256
		.amdhsa_reserve_vcc 1
		.amdhsa_float_round_mode_32 0
		.amdhsa_float_round_mode_16_64 0
		.amdhsa_float_denorm_mode_32 3
		.amdhsa_float_denorm_mode_16_64 3
		.amdhsa_dx10_clamp 1
		.amdhsa_ieee_mode 1
		.amdhsa_fp16_overflow 0
		.amdhsa_tg_split 0
		.amdhsa_exception_fp_ieee_invalid_op 0
		.amdhsa_exception_fp_denorm_src 0
		.amdhsa_exception_fp_ieee_div_zero 0
		.amdhsa_exception_fp_ieee_overflow 0
		.amdhsa_exception_fp_ieee_underflow 0
		.amdhsa_exception_fp_ieee_inexact 0
		.amdhsa_exception_int_div_zero 0
	.end_amdhsa_kernel

; __global__ void __launch_bounds__(512) mk_fwd(Params p0) {
amdhsa.kernels:
  - .agpr_count:     0
    .args:
      - .offset:         0
        .size:           192
        .value_kind:     by_value
      - .offset:         192
        .size:           4
        .value_kind:     hidden_block_count_x
      - .offset:         196
        .size:           4
        .value_kind:     hidden_block_count_y
      - .offset:         200
        .size:           4
        .value_kind:     hidden_block_count_z
      - .offset:         204
        .size:           2
        .value_kind:     hidden_group_size_x
      - .offset:         206
        .size:           2
        .value_kind:     hidden_group_size_y
      - .offset:         208
        .size:           2
        .value_kind:     hidden_group_size_z
      - .offset:         210
        .size:           2
        .value_kind:     hidden_remainder_x
      - .offset:         212
        .size:           2
        .value_kind:     hidden_remainder_y
      - .offset:         214
        .size:           2
        .value_kind:     hidden_remainder_z
      - .offset:         232
        .size:           8
        .value_kind:     hidden_global_offset_x
      - .offset:         240
        .size:           8
        .value_kind:     hidden_global_offset_y
      - .offset:         248
        .size:           8
        .value_kind:     hidden_global_offset_z
      - .offset:         256
        .size:           2
        .value_kind:     hidden_grid_dims
      - .offset:         280
        .size:           8
        .value_kind:     hidden_multigrid_sync_arg
      - .offset:         312
        .size:           4
        .value_kind:     hidden_dynamic_lds_size
    .group_segment_fixed_size: 0
    .kernarg_segment_align: 8
    .kernarg_segment_size: 448
    .language:       OpenCL C
    .language_version:
      - 2
      - 0
    .max_flat_workgroup_size: 512
    .name:           _Z6mk_fwd6Params
    .private_segment_fixed_size: 0
    .sgpr_count:     106
    .sgpr_spill_count: 237
    .symbol:         _Z6mk_fwd6Params.kd
    .uniform_work_group_size: 1
    .uses_dynamic_stack: false
    .vgpr_count:     256
    .vgpr_spill_count: 0
    .wavefront_size: 64
